# P2b start state pipelined (decay vector + four segment states requested together, rolling depth 4); one conv pair per P2b unit, pairs 256..287 run in P2 on workgroups 0..31
# speedup vs baseline: 1.0010x; 1.0010x over previous
; __global__ void __launch_bounds__(512, 2) hymba_fwd(Params p) {
;     ...
;         for (int u = CONV_MOVED + bx; u < NB * (SEQ / 16) / 2; u += G) conv_pair<16>(p, lds, false, 2 * u + (threadIdx.x >> 8));
;         { const int ib = G - 1 - bx, nb2 = G < 32 ? G : 32;
;           if (ib < nb2) for (int u = ib; u < DB / 2; u += nb2) conv_pair<DS>(p, lds, true, 2 * u + (threadIdx.x >> 8)); }
.Lp2_conv:
	s_mov_b32 s100, 0
	s_cmpk_lt_i32 s2, 0x100
	s_cselect_b64 s[28:29], -1, 0
	s_cmpk_gt_i32 s2, 0xdf
	s_cbranch_scc1 .LBB0_400
	v_lshl_add_u32 v0, s2, 1, v96
	v_add_u32_e32 v89, 0x240, v0
	v_lshlrev_b32_e32 v0, 4, v96
	v_lshl_add_u32 v0, s2, 5, v0
	s_add_i32 s1, s2, 0x120
	s_lshl_b32 s3, s66, 1
	v_add_u32_e32 v90, 0x2403, v0
	s_lshl_b32 s10, s66, 5
	v_mov_b32_e32 v17, 0
	v_mov_b32_e32 v91, 0x358637bd
	s_mov_b32 s11, 0x800000
	s_mov_b32 s12, 0x96f6000
	s_branch .LBB0_336
.LBB0_335:
	s_or_b64 exec, exec, s[6:7]
	s_waitcnt lgkmcnt(0)
	s_barrier
	s_cmp_lg_u32 s100, 0
	s_cbranch_scc1 .Lp2_noextra
	s_cmp_gt_u32 s2, 31
	s_cbranch_scc1 .Lp2_noextra
	s_mov_b32 s100, 1
	v_subrev_u32_e32 v89, 64, v89
	s_branch .LBB0_336
.Lp2_noextra:
	s_add_i32 s1, s1, s66
	v_add_u32_e32 v89, s3, v89
	s_cmpk_gt_i32 s1, 0x1ff
	v_add_u32_e32 v90, s10, v90
	s_cbranch_scc1 .LBB0_400

; #define LDS_BARRIER() do { asm volatile("s_waitcnt lgkmcnt(0)" ::: "memory"); __builtin_amdgcn_s_barrier(); asm volatile("" ::: "memory"); } while (0)
; template <bool FULL>
; __device__ __forceinline__ void hgrn_seg(const Params& p, unsigned char* lds, int b, int h, int seg) {
;     ...
;     if (FULL && seg > 0) {
;         float* dl = (float*)(lds + H_P);
;         for (int idx = tid; idx < seg * DK; idx += 512) dl[idx] = SDEC[(size_t)bh * NSEG * DK + idx];
;         LDS_BARRIER();
;         const float* sl0 = SLOC + (size_t)bh * NSEG * DK * DV + (size_t)(w * 8 * 64 + lane) * 4;
; #pragma unroll 2
;         for (int j = 0; j < seg; ++j) { const float* sl = sl0 + (size_t)j * DK * DV; const float* dj = dl + j * DK + 64 * kh + 4 * hh;
; #pragma unroll
;             for (int a = 0; a < 2; ++a)
; #pragma unroll
;                 for (int g = 0; g < 4; ++g) { const f32x4 d4 = *(const f32x4*)(dj + 32 * a + 8 * g), s4 = *(const f32x4*)(sl + (a * 4 + g) * 256);
; #pragma unroll
;                     for (int i = 0; i < 4; ++i) S[a][4 * g + i] = d4[i] * S[a][4 * g + i] + s4[i]; } }
;         LDS_BARRIER();
.LBB0_462:
	s_ashr_i32 s64, s97, 5
	s_bfe_u32 s4, s97, 0x20003
	v_readfirstlane_b32 s51, v176
	s_lshl_b32 s66, s64, 2
	s_lshr_b32 s48, s97, 3
	s_and_b32 s50, s93, 7
	s_and_b32 s49, s97, 7
	s_lshr_b32 s95, s51, 6
	s_or_b32 s46, s66, s4
	s_cmp_lg_u32 s49, 0
	s_cbranch_scc0 .LBB0_549
	s_lshl_b32 s47, s49, 7
	s_lshl_b32 s60, s95, 9
	s_and_b32 s65, s51, 0xffffff00
	s_mov_b32 s57, s87
	v_readlane_b32 s66, v247, 50
	v_readlane_b32 s67, v247, 51
	s_lshl_b32 s70, s46, 19
	s_add_u32 s66, s66, s70
	s_addc_u32 s67, s67, 0
	s_mov_b64 s[70:71], s[66:67]
	v_add_u32_e32 v32, s60, v206
	v_lshlrev_b32_e32 v32, 4, v32
	v_add_u32_e32 v33, 0x1000, v32
	v_add_u32_e32 v34, s65, v129
	s_waitcnt vmcnt(0)
	global_load_dwordx4 v[40:43], v32, s[70:71]
	global_load_dwordx4 v[44:47], v32, s[70:71] offset:1024
	global_load_dwordx4 v[60:63], v32, s[70:71] offset:2048
	global_load_dwordx4 v[64:67], v32, s[70:71] offset:3072
	global_load_dwordx4 v[68:71], v33, s[70:71]
	global_load_dwordx4 v[72:75], v33, s[70:71] offset:1024
	global_load_dwordx4 v[76:79], v33, s[70:71] offset:2048
	global_load_dwordx4 v[80:83], v33, s[70:71] offset:3072
	s_add_u32 s70, s70, 0x10000
	s_addc_u32 s71, s71, 0
	s_cmp_lt_u32 s49, 2
	s_cbranch_scc1 .Lss_issued
	global_load_dwordx4 v[84:87], v32, s[70:71]
	global_load_dwordx4 v[88:91], v32, s[70:71] offset:1024
	global_load_dwordx4 v[92:95], v32, s[70:71] offset:2048
	global_load_dwordx4 v[136:139], v32, s[70:71] offset:3072
	global_load_dwordx4 v[140:143], v33, s[70:71]
	global_load_dwordx4 v[144:147], v33, s[70:71] offset:1024
	global_load_dwordx4 v[148:151], v33, s[70:71] offset:2048
	global_load_dwordx4 v[152:155], v33, s[70:71] offset:3072
	s_add_u32 s70, s70, 0x10000
	s_addc_u32 s71, s71, 0
	s_cmp_lt_u32 s49, 3
	s_cbranch_scc1 .Lss_issued
	global_load_dwordx4 v[156:159], v32, s[70:71]
	global_load_dwordx4 v[160:163], v32, s[70:71] offset:1024
	global_load_dwordx4 v[164:167], v32, s[70:71] offset:2048
	global_load_dwordx4 v[168:171], v32, s[70:71] offset:3072
	global_load_dwordx4 v[172:175], v33, s[70:71]
	global_load_dwordx4 v[180:183], v33, s[70:71] offset:1024
	global_load_dwordx4 v[184:187], v33, s[70:71] offset:2048
	global_load_dwordx4 v[188:191], v33, s[70:71] offset:3072
	s_add_u32 s70, s70, 0x10000
	s_addc_u32 s71, s71, 0
	s_cmp_lt_u32 s49, 4
	s_cbranch_scc1 .Lss_issued
	global_load_dwordx4 v[192:195], v32, s[70:71]
	global_load_dwordx4 v[196:199], v32, s[70:71] offset:1024
	global_load_dwordx4 v[200:203], v32, s[70:71] offset:2048
	global_load_dwordx4 v[208:211], v32, s[70:71] offset:3072
	global_load_dwordx4 v[212:215], v33, s[70:71]
	global_load_dwordx4 v[216:219], v33, s[70:71] offset:1024
	global_load_dwordx4 v[220:223], v33, s[70:71] offset:2048
	global_load_dwordx4 v[224:227], v33, s[70:71] offset:3072
	s_add_u32 s70, s70, 0x10000
	s_addc_u32 s71, s71, 0
.Lss_issued:
	s_lshl_b32 s52, s46, 12
	s_mov_b32 s53, 0
	v_lshl_add_u64 v[36:37], v[58:59], 0, s[52:53]
	v_cmp_gt_u32_e32 vcc, s47, v176
	s_and_saveexec_b64 s[62:63], vcc
	global_load_dword v38, v[36:37], off
	v_add_u32_e32 v35, 0x200, v176
	v_cmp_gt_u32_e32 vcc, s47, v35
	s_and_saveexec_b64 s[54:55], vcc
	global_load_dword v39, v[36:37], off offset:2048
	s_waitcnt vmcnt(0)
	ds_write_b32 v128, v39 offset:2048
	s_mov_b64 exec, s[54:55]
	ds_write_b32 v128, v38
	s_mov_b64 exec, s[62:63]
	v_mov_b32_e32 v0, 0
	v_mov_b32_e32 v1, 0
	v_mov_b32_e32 v2, 0
	v_mov_b32_e32 v3, 0
	v_mov_b32_e32 v4, 0
	v_mov_b32_e32 v5, 0
	v_mov_b32_e32 v6, 0
	v_mov_b32_e32 v7, 0
	v_mov_b32_e32 v8, 0
	v_mov_b32_e32 v9, 0
	v_mov_b32_e32 v10, 0
	v_mov_b32_e32 v11, 0
	v_mov_b32_e32 v12, 0
	v_mov_b32_e32 v13, 0
	v_mov_b32_e32 v14, 0
	v_mov_b32_e32 v15, 0
	v_mov_b32_e32 v16, 0
	v_mov_b32_e32 v17, 0
	v_mov_b32_e32 v18, 0
	v_mov_b32_e32 v19, 0
	v_mov_b32_e32 v20, 0
	v_mov_b32_e32 v21, 0
	v_mov_b32_e32 v22, 0
	v_mov_b32_e32 v23, 0
	v_mov_b32_e32 v24, 0
	v_mov_b32_e32 v25, 0
	v_mov_b32_e32 v26, 0
	v_mov_b32_e32 v27, 0
	v_mov_b32_e32 v28, 0
	v_mov_b32_e32 v29, 0
	v_mov_b32_e32 v30, 0
	v_mov_b32_e32 v31, 0
	s_waitcnt lgkmcnt(0)
	s_barrier
	ds_read_b128 v[228:231], v34 offset:0
	ds_read_b128 v[232:235], v34 offset:32
	ds_read_b128 v[236:239], v34 offset:64
	ds_read_b128 v[240:243], v34 offset:96
	s_waitcnt lgkmcnt(3)
	v_pk_fma_f32 v[16:17], v[16:17], v[228:229], v[40:41]
	v_pk_fma_f32 v[18:19], v[18:19], v[230:231], v[42:43]
	s_waitcnt lgkmcnt(2)
	v_pk_fma_f32 v[20:21], v[20:21], v[232:233], v[44:45]
	v_pk_fma_f32 v[22:23], v[22:23], v[234:235], v[46:47]
	s_waitcnt lgkmcnt(1)
	v_pk_fma_f32 v[24:25], v[24:25], v[236:237], v[60:61]
	v_pk_fma_f32 v[26:27], v[26:27], v[238:239], v[62:63]
	s_waitcnt lgkmcnt(0)
	v_pk_fma_f32 v[28:29], v[28:29], v[240:241], v[64:65]
	v_pk_fma_f32 v[30:31], v[30:31], v[242:243], v[66:67]
	ds_read_b128 v[228:231], v34 offset:128
	ds_read_b128 v[232:235], v34 offset:160
	ds_read_b128 v[236:239], v34 offset:192
	ds_read_b128 v[240:243], v34 offset:224
	s_waitcnt lgkmcnt(3)
	v_pk_fma_f32 v[0:1], v[0:1], v[228:229], v[68:69]
	v_pk_fma_f32 v[2:3], v[2:3], v[230:231], v[70:71]
	s_waitcnt lgkmcnt(2)
	v_pk_fma_f32 v[4:5], v[4:5], v[232:233], v[72:73]
	v_pk_fma_f32 v[6:7], v[6:7], v[234:235], v[74:75]
	s_waitcnt lgkmcnt(1)
	v_pk_fma_f32 v[8:9], v[8:9], v[236:237], v[76:77]
	v_pk_fma_f32 v[10:11], v[10:11], v[238:239], v[78:79]
	s_waitcnt lgkmcnt(0)
	v_pk_fma_f32 v[12:13], v[12:13], v[240:241], v[80:81]
	v_pk_fma_f32 v[14:15], v[14:15], v[242:243], v[82:83]
	s_cmp_lt_u32 s49, 5
	s_cbranch_scc1 .Lss_ni0
	global_load_dwordx4 v[40:43], v32, s[70:71]
	global_load_dwordx4 v[44:47], v32, s[70:71] offset:1024
	global_load_dwordx4 v[60:63], v32, s[70:71] offset:2048
	global_load_dwordx4 v[64:67], v32, s[70:71] offset:3072
	global_load_dwordx4 v[68:71], v33, s[70:71]
	global_load_dwordx4 v[72:75], v33, s[70:71] offset:1024
	global_load_dwordx4 v[76:79], v33, s[70:71] offset:2048
	global_load_dwordx4 v[80:83], v33, s[70:71] offset:3072
	s_add_u32 s70, s70, 0x10000
	s_addc_u32 s71, s71, 0
; template <bool FULL>
; __device__ __forceinline__ void hgrn_seg(const Params& p, unsigned char* lds, int b, int h, int seg) {
;     ...
; #pragma unroll 2
;         for (int j = 0; j < seg; ++j) { const float* sl = sl0 + (size_t)j * DK * DV; const float* dj = dl + j * DK + 64 * kh + 4 * hh;
; #pragma unroll
;             for (int a = 0; a < 2; ++a)
; #pragma unroll
;                 for (int g = 0; g < 4; ++g) { const f32x4 d4 = *(const f32x4*)(dj + 32 * a + 8 * g), s4 = *(const f32x4*)(sl + (a * 4 + g) * 256);
; #pragma unroll
;                     for (int i = 0; i < 4; ++i) S[a][4 * g + i] = d4[i] * S[a][4 * g + i] + s4[i]; } }
.Lss_ni0:
	s_cmp_lt_u32 s49, 2
	s_cbranch_scc1 .Lss_done
	ds_read_b128 v[228:231], v34 offset:512
	ds_read_b128 v[232:235], v34 offset:544
	ds_read_b128 v[236:239], v34 offset:576
	ds_read_b128 v[240:243], v34 offset:608
	s_waitcnt lgkmcnt(3)
	v_pk_fma_f32 v[16:17], v[16:17], v[228:229], v[84:85]
	v_pk_fma_f32 v[18:19], v[18:19], v[230:231], v[86:87]
	s_waitcnt lgkmcnt(2)
	v_pk_fma_f32 v[20:21], v[20:21], v[232:233], v[88:89]
	v_pk_fma_f32 v[22:23], v[22:23], v[234:235], v[90:91]
	s_waitcnt lgkmcnt(1)
	v_pk_fma_f32 v[24:25], v[24:25], v[236:237], v[92:93]
	v_pk_fma_f32 v[26:27], v[26:27], v[238:239], v[94:95]
	s_waitcnt lgkmcnt(0)
	v_pk_fma_f32 v[28:29], v[28:29], v[240:241], v[136:137]
	v_pk_fma_f32 v[30:31], v[30:31], v[242:243], v[138:139]
	ds_read_b128 v[228:231], v34 offset:640
	ds_read_b128 v[232:235], v34 offset:672
	ds_read_b128 v[236:239], v34 offset:704
	ds_read_b128 v[240:243], v34 offset:736
	s_waitcnt lgkmcnt(3)
	v_pk_fma_f32 v[0:1], v[0:1], v[228:229], v[140:141]
	v_pk_fma_f32 v[2:3], v[2:3], v[230:231], v[142:143]
	s_waitcnt lgkmcnt(2)
	v_pk_fma_f32 v[4:5], v[4:5], v[232:233], v[144:145]
	v_pk_fma_f32 v[6:7], v[6:7], v[234:235], v[146:147]
	s_waitcnt lgkmcnt(1)
	v_pk_fma_f32 v[8:9], v[8:9], v[236:237], v[148:149]
	v_pk_fma_f32 v[10:11], v[10:11], v[238:239], v[150:151]
	s_waitcnt lgkmcnt(0)
	v_pk_fma_f32 v[12:13], v[12:13], v[240:241], v[152:153]
	v_pk_fma_f32 v[14:15], v[14:15], v[242:243], v[154:155]
	s_cmp_lt_u32 s49, 6
	s_cbranch_scc1 .Lss_ni1
	global_load_dwordx4 v[84:87], v32, s[70:71]
	global_load_dwordx4 v[88:91], v32, s[70:71] offset:1024
	global_load_dwordx4 v[92:95], v32, s[70:71] offset:2048
	global_load_dwordx4 v[136:139], v32, s[70:71] offset:3072
	global_load_dwordx4 v[140:143], v33, s[70:71]
	global_load_dwordx4 v[144:147], v33, s[70:71] offset:1024
	global_load_dwordx4 v[148:151], v33, s[70:71] offset:2048
	global_load_dwordx4 v[152:155], v33, s[70:71] offset:3072
	s_add_u32 s70, s70, 0x10000
	s_addc_u32 s71, s71, 0
.Lss_ni1:
	s_cmp_lt_u32 s49, 3
	s_cbranch_scc1 .Lss_done
	ds_read_b128 v[228:231], v34 offset:1024
	ds_read_b128 v[232:235], v34 offset:1056
	ds_read_b128 v[236:239], v34 offset:1088
	ds_read_b128 v[240:243], v34 offset:1120
	s_waitcnt lgkmcnt(3)
	v_pk_fma_f32 v[16:17], v[16:17], v[228:229], v[156:157]
	v_pk_fma_f32 v[18:19], v[18:19], v[230:231], v[158:159]
	s_waitcnt lgkmcnt(2)
	v_pk_fma_f32 v[20:21], v[20:21], v[232:233], v[160:161]
	v_pk_fma_f32 v[22:23], v[22:23], v[234:235], v[162:163]
	s_waitcnt lgkmcnt(1)
	v_pk_fma_f32 v[24:25], v[24:25], v[236:237], v[164:165]
	v_pk_fma_f32 v[26:27], v[26:27], v[238:239], v[166:167]
	s_waitcnt lgkmcnt(0)
	v_pk_fma_f32 v[28:29], v[28:29], v[240:241], v[168:169]
	v_pk_fma_f32 v[30:31], v[30:31], v[242:243], v[170:171]
	ds_read_b128 v[228:231], v34 offset:1152
	ds_read_b128 v[232:235], v34 offset:1184
	ds_read_b128 v[236:239], v34 offset:1216
	ds_read_b128 v[240:243], v34 offset:1248
	s_waitcnt lgkmcnt(3)
	v_pk_fma_f32 v[0:1], v[0:1], v[228:229], v[172:173]
	v_pk_fma_f32 v[2:3], v[2:3], v[230:231], v[174:175]
	s_waitcnt lgkmcnt(2)
	v_pk_fma_f32 v[4:5], v[4:5], v[232:233], v[180:181]
	v_pk_fma_f32 v[6:7], v[6:7], v[234:235], v[182:183]
	s_waitcnt lgkmcnt(1)
	v_pk_fma_f32 v[8:9], v[8:9], v[236:237], v[184:185]
	v_pk_fma_f32 v[10:11], v[10:11], v[238:239], v[186:187]
	s_waitcnt lgkmcnt(0)
	v_pk_fma_f32 v[12:13], v[12:13], v[240:241], v[188:189]
	v_pk_fma_f32 v[14:15], v[14:15], v[242:243], v[190:191]
	s_cmp_lt_u32 s49, 7
	s_cbranch_scc1 .Lss_ni2
	global_load_dwordx4 v[156:159], v32, s[70:71]
	global_load_dwordx4 v[160:163], v32, s[70:71] offset:1024
	global_load_dwordx4 v[164:167], v32, s[70:71] offset:2048
	global_load_dwordx4 v[168:171], v32, s[70:71] offset:3072
	global_load_dwordx4 v[172:175], v33, s[70:71]
	global_load_dwordx4 v[180:183], v33, s[70:71] offset:1024
	global_load_dwordx4 v[184:187], v33, s[70:71] offset:2048
	global_load_dwordx4 v[188:191], v33, s[70:71] offset:3072
	s_add_u32 s70, s70, 0x10000
	s_addc_u32 s71, s71, 0
; #define LDS_BARRIER() do { asm volatile("s_waitcnt lgkmcnt(0)" ::: "memory"); __builtin_amdgcn_s_barrier(); asm volatile("" ::: "memory"); } while (0)
; template <bool FULL>
; __device__ __forceinline__ void hgrn_seg(const Params& p, unsigned char* lds, int b, int h, int seg) {
;     ...
; #pragma unroll 2
;         for (int j = 0; j < seg; ++j) { const float* sl = sl0 + (size_t)j * DK * DV; const float* dj = dl + j * DK + 64 * kh + 4 * hh;
; #pragma unroll
;             for (int a = 0; a < 2; ++a)
; #pragma unroll
;                 for (int g = 0; g < 4; ++g) { const f32x4 d4 = *(const f32x4*)(dj + 32 * a + 8 * g), s4 = *(const f32x4*)(sl + (a * 4 + g) * 256);
; #pragma unroll
;                     for (int i = 0; i < 4; ++i) S[a][4 * g + i] = d4[i] * S[a][4 * g + i] + s4[i]; } }
;         LDS_BARRIER();
.Lss_ni2:
	s_cmp_lt_u32 s49, 4
	s_cbranch_scc1 .Lss_done
	ds_read_b128 v[228:231], v34 offset:1536
	ds_read_b128 v[232:235], v34 offset:1568
	ds_read_b128 v[236:239], v34 offset:1600
	ds_read_b128 v[240:243], v34 offset:1632
	s_waitcnt lgkmcnt(3)
	v_pk_fma_f32 v[16:17], v[16:17], v[228:229], v[192:193]
	v_pk_fma_f32 v[18:19], v[18:19], v[230:231], v[194:195]
	s_waitcnt lgkmcnt(2)
	v_pk_fma_f32 v[20:21], v[20:21], v[232:233], v[196:197]
	v_pk_fma_f32 v[22:23], v[22:23], v[234:235], v[198:199]
	s_waitcnt lgkmcnt(1)
	v_pk_fma_f32 v[24:25], v[24:25], v[236:237], v[200:201]
	v_pk_fma_f32 v[26:27], v[26:27], v[238:239], v[202:203]
	s_waitcnt lgkmcnt(0)
	v_pk_fma_f32 v[28:29], v[28:29], v[240:241], v[208:209]
	v_pk_fma_f32 v[30:31], v[30:31], v[242:243], v[210:211]
	ds_read_b128 v[228:231], v34 offset:1664
	ds_read_b128 v[232:235], v34 offset:1696
	ds_read_b128 v[236:239], v34 offset:1728
	ds_read_b128 v[240:243], v34 offset:1760
	s_waitcnt lgkmcnt(3)
	v_pk_fma_f32 v[0:1], v[0:1], v[228:229], v[212:213]
	v_pk_fma_f32 v[2:3], v[2:3], v[230:231], v[214:215]
	s_waitcnt lgkmcnt(2)
	v_pk_fma_f32 v[4:5], v[4:5], v[232:233], v[216:217]
	v_pk_fma_f32 v[6:7], v[6:7], v[234:235], v[218:219]
	s_waitcnt lgkmcnt(1)
	v_pk_fma_f32 v[8:9], v[8:9], v[236:237], v[220:221]
	v_pk_fma_f32 v[10:11], v[10:11], v[238:239], v[222:223]
	s_waitcnt lgkmcnt(0)
	v_pk_fma_f32 v[12:13], v[12:13], v[240:241], v[224:225]
	v_pk_fma_f32 v[14:15], v[14:15], v[242:243], v[226:227]
	s_cmp_lt_u32 s49, 5
	s_cbranch_scc1 .Lss_done
	s_waitcnt vmcnt(0)
	ds_read_b128 v[228:231], v34 offset:2048
	ds_read_b128 v[232:235], v34 offset:2080
	ds_read_b128 v[236:239], v34 offset:2112
	ds_read_b128 v[240:243], v34 offset:2144
	s_waitcnt lgkmcnt(3)
	v_pk_fma_f32 v[16:17], v[16:17], v[228:229], v[40:41]
	v_pk_fma_f32 v[18:19], v[18:19], v[230:231], v[42:43]
	s_waitcnt lgkmcnt(2)
	v_pk_fma_f32 v[20:21], v[20:21], v[232:233], v[44:45]
	v_pk_fma_f32 v[22:23], v[22:23], v[234:235], v[46:47]
	s_waitcnt lgkmcnt(1)
	v_pk_fma_f32 v[24:25], v[24:25], v[236:237], v[60:61]
	v_pk_fma_f32 v[26:27], v[26:27], v[238:239], v[62:63]
	s_waitcnt lgkmcnt(0)
	v_pk_fma_f32 v[28:29], v[28:29], v[240:241], v[64:65]
	v_pk_fma_f32 v[30:31], v[30:31], v[242:243], v[66:67]
	ds_read_b128 v[228:231], v34 offset:2176
	ds_read_b128 v[232:235], v34 offset:2208
	ds_read_b128 v[236:239], v34 offset:2240
	ds_read_b128 v[240:243], v34 offset:2272
	s_waitcnt lgkmcnt(3)
	v_pk_fma_f32 v[0:1], v[0:1], v[228:229], v[68:69]
	v_pk_fma_f32 v[2:3], v[2:3], v[230:231], v[70:71]
	s_waitcnt lgkmcnt(2)
	v_pk_fma_f32 v[4:5], v[4:5], v[232:233], v[72:73]
	v_pk_fma_f32 v[6:7], v[6:7], v[234:235], v[74:75]
	s_waitcnt lgkmcnt(1)
	v_pk_fma_f32 v[8:9], v[8:9], v[236:237], v[76:77]
	v_pk_fma_f32 v[10:11], v[10:11], v[238:239], v[78:79]
	s_waitcnt lgkmcnt(0)
	v_pk_fma_f32 v[12:13], v[12:13], v[240:241], v[80:81]
	v_pk_fma_f32 v[14:15], v[14:15], v[242:243], v[82:83]
	s_cmp_lt_u32 s49, 6
	s_cbranch_scc1 .Lss_done
	ds_read_b128 v[228:231], v34 offset:2560
	ds_read_b128 v[232:235], v34 offset:2592
	ds_read_b128 v[236:239], v34 offset:2624
	ds_read_b128 v[240:243], v34 offset:2656
	s_waitcnt lgkmcnt(3)
	v_pk_fma_f32 v[16:17], v[16:17], v[228:229], v[84:85]
	v_pk_fma_f32 v[18:19], v[18:19], v[230:231], v[86:87]
	s_waitcnt lgkmcnt(2)
	v_pk_fma_f32 v[20:21], v[20:21], v[232:233], v[88:89]
	v_pk_fma_f32 v[22:23], v[22:23], v[234:235], v[90:91]
	s_waitcnt lgkmcnt(1)
	v_pk_fma_f32 v[24:25], v[24:25], v[236:237], v[92:93]
	v_pk_fma_f32 v[26:27], v[26:27], v[238:239], v[94:95]
	s_waitcnt lgkmcnt(0)
	v_pk_fma_f32 v[28:29], v[28:29], v[240:241], v[136:137]
	v_pk_fma_f32 v[30:31], v[30:31], v[242:243], v[138:139]
	ds_read_b128 v[228:231], v34 offset:2688
	ds_read_b128 v[232:235], v34 offset:2720
	ds_read_b128 v[236:239], v34 offset:2752
	ds_read_b128 v[240:243], v34 offset:2784
	s_waitcnt lgkmcnt(3)
	v_pk_fma_f32 v[0:1], v[0:1], v[228:229], v[140:141]
	v_pk_fma_f32 v[2:3], v[2:3], v[230:231], v[142:143]
	s_waitcnt lgkmcnt(2)
	v_pk_fma_f32 v[4:5], v[4:5], v[232:233], v[144:145]
	v_pk_fma_f32 v[6:7], v[6:7], v[234:235], v[146:147]
	s_waitcnt lgkmcnt(1)
	v_pk_fma_f32 v[8:9], v[8:9], v[236:237], v[148:149]
	v_pk_fma_f32 v[10:11], v[10:11], v[238:239], v[150:151]
	s_waitcnt lgkmcnt(0)
	v_pk_fma_f32 v[12:13], v[12:13], v[240:241], v[152:153]
	v_pk_fma_f32 v[14:15], v[14:15], v[242:243], v[154:155]
	s_cmp_lt_u32 s49, 7
	s_cbranch_scc1 .Lss_done
	ds_read_b128 v[228:231], v34 offset:3072
	ds_read_b128 v[232:235], v34 offset:3104
	ds_read_b128 v[236:239], v34 offset:3136
	ds_read_b128 v[240:243], v34 offset:3168
	s_waitcnt lgkmcnt(3)
	v_pk_fma_f32 v[16:17], v[16:17], v[228:229], v[156:157]
	v_pk_fma_f32 v[18:19], v[18:19], v[230:231], v[158:159]
	s_waitcnt lgkmcnt(2)
	v_pk_fma_f32 v[20:21], v[20:21], v[232:233], v[160:161]
	v_pk_fma_f32 v[22:23], v[22:23], v[234:235], v[162:163]
	s_waitcnt lgkmcnt(1)
	v_pk_fma_f32 v[24:25], v[24:25], v[236:237], v[164:165]
	v_pk_fma_f32 v[26:27], v[26:27], v[238:239], v[166:167]
	s_waitcnt lgkmcnt(0)
	v_pk_fma_f32 v[28:29], v[28:29], v[240:241], v[168:169]
	v_pk_fma_f32 v[30:31], v[30:31], v[242:243], v[170:171]
	ds_read_b128 v[228:231], v34 offset:3200
	ds_read_b128 v[232:235], v34 offset:3232
	ds_read_b128 v[236:239], v34 offset:3264
	ds_read_b128 v[240:243], v34 offset:3296
	s_waitcnt lgkmcnt(3)
	v_pk_fma_f32 v[0:1], v[0:1], v[228:229], v[172:173]
	v_pk_fma_f32 v[2:3], v[2:3], v[230:231], v[174:175]
	s_waitcnt lgkmcnt(2)
	v_pk_fma_f32 v[4:5], v[4:5], v[232:233], v[180:181]
	v_pk_fma_f32 v[6:7], v[6:7], v[234:235], v[182:183]
	s_waitcnt lgkmcnt(1)
	v_pk_fma_f32 v[8:9], v[8:9], v[236:237], v[184:185]
	v_pk_fma_f32 v[10:11], v[10:11], v[238:239], v[186:187]
	s_waitcnt lgkmcnt(0)
	v_pk_fma_f32 v[12:13], v[12:13], v[240:241], v[188:189]
	v_pk_fma_f32 v[14:15], v[14:15], v[242:243], v[190:191]
.Lss_done:
	v_or_b32_e32 v60, s60, v206

; __global__ void __launch_bounds__(512, 2) hymba_fwd(Params p) {
;     ...
;         for (int u = bx; u < NB * HEADS * NSEG; u += G) { hgrn_seg<true>(p, lds, u >> 5, (u >> 3) & 3, u & 7);
;             const int seg = u & 7, ne = seg < 2 ? 2 : (seg < 6 ? 1 : 0), o0 = (int)((0x88765420u >> (4 * seg)) & 15u);
;             for (int k = 0; k < ne; ++k) conv_pair<16>(p, lds, false, 2 * ((u >> 3) * 8 + o0 + k) + (threadIdx.x >> 8)); }
.LBB0_482:
	s_cmp_lt_u32 s49, 8
	s_cselect_b64 s[46:47], -1, 0
	v_cndmask_b32_e64 v0, 0, 1, s[46:47]
	s_waitcnt lgkmcnt(0)
	s_barrier
	s_cmp_gt_u32 s49, 0
	v_readfirstlane_b32 s4, v0
	s_mov_b32 s4, 1
	v_readlane_b32 s64, v247, 38
	v_readlane_b32 s52, v247, 36
	s_cmp_eq_u32 s4, 0
	v_readlane_b32 s65, v247, 39
	v_readlane_b32 s66, v247, 40
	v_readlane_b32 s67, v247, 41
	v_readlane_b32 s53, v247, 37
	s_cbranch_scc1 .LBB0_461
	s_lshl_b32 s46, s48, 4
	s_lshl_b32 s47, s48, 8
	s_cmp_eq_u32 s49, 8
	s_cbranch_scc1 .Lp2b_seg6
	s_lshl_b32 s48, s49, 2
	s_lshr_b32 s48, 0x76543210, s48
	s_and_b32 s49, s48, 15
	s_lshl_b32 s48, s4, 5
	s_lshl_b32 s4, s49, 1
	s_add_i32 s4, s4, s46
	v_add_u32_e32 v136, s4, v96
	s_lshl_b32 s4, s49, 5
	s_add_i32 s4, s4, s47
	v_add_u32_e32 v137, s4, v130
	s_mov_b32 s49, 0
	s_branch .LBB0_485

; __device__ __forceinline__ unsigned xb_ld(unsigned* p)              { return __hip_atomic_load(p, __ATOMIC_RELAXED, __HIP_MEMORY_SCOPE_AGENT); }
; __device__ __forceinline__ unsigned xb_add(unsigned* p, unsigned v) { return __hip_atomic_fetch_add(p, v, __ATOMIC_RELAXED, __HIP_MEMORY_SCOPE_AGENT); }
; __device__ __forceinline__ void xcd_barrier_complete(unsigned* bar, unsigned x, unsigned& nloc, unsigned& nx) {
;     const unsigned G = gridDim.x * gridDim.y * gridDim.z;
;     unsigned sum, cnt, mine, sp = 0u;
;     for (;;) {
;         sum = 0u; cnt = 0u; mine = 0u;
; #pragma unroll
;         for (unsigned j = 0; j < 16; ++j) { const unsigned c = xb_ld(&bar[XB_XCNT(j)]); sum += c; cnt += (c > 0u) ? 1u : 0u; mine = (j == x) ? c : mine; }
;         if (sum == G) break;
;         __builtin_amdgcn_s_sleep(1);
;         if ((++sp & 255u) == 0u) { if (xb_ld(&bar[XB_TMO])) break; if (sp > XB_SPIN_CAP) { atomicAdd(&bar[XB_TMO], 1u); break; } }
;     }
;     nloc = mine > 0u ? mine : 1u; nx = cnt > 0u ? cnt : 1u;
; }
; __device__ __forceinline__ void xcd_barrier(const XcdBarrier& b) {
;     asm volatile("s_waitcnt vmcnt(0)" ::: "memory");
;     __syncthreads();
;     if (threadIdx.x == 0) {
;         unsigned* bar = b.bar;
;         __builtin_amdgcn_s_waitcnt(0);
;         unsigned nloc = b.st[0], nx = b.st[1];
;         if (nloc == 0u) { xcd_barrier_complete(bar, b.x, nloc, nx); b.st[0] = nloc; b.st[1] = nx; }
;         const unsigned old = xb_add(&bar[XB_XSUB(b.x)], 1u);
;         const unsigned gen = old / nloc;
.LBB0_549:
	s_mov_b32 s57, s87
	s_cbranch_execnz .LBB0_472
	s_branch .LBB0_473
.LBB0_551:
	s_waitcnt vmcnt(0)
	v_readlane_b32 s72, v247, 42
	v_readlane_b32 s73, v247, 43
	s_waitcnt lgkmcnt(0)
	s_barrier
	s_and_saveexec_b64 s[6:7], s[72:73]
	v_readlane_b32 s70, v247, 45
	v_readlane_b32 s86, v247, 34
	v_readlane_b32 s74, v247, 32
	v_readlane_b32 s78, v247, 48
	v_readlane_b32 s76, v247, 47
	v_readlane_b32 s71, v247, 46
	v_readlane_b32 s77, v247, 44
	v_readlane_b32 s87, v247, 35
	v_readlane_b32 s75, v247, 33
	v_readlane_b32 s79, v247, 49
	s_cbranch_execz .LBB0_603
	s_add_i32 s0, 0, 0x22c00
	s_waitcnt vmcnt(3)
	v_mov_b32_e32 v0, s0
	s_waitcnt vmcnt(0) expcnt(0) lgkmcnt(0)
	ds_read_b32 v2, v0
	s_add_i32 s0, 0, 0x22c04
	v_mov_b32_e32 v0, s0
	ds_read_b32 v0, v0
	s_waitcnt lgkmcnt(1)
	v_cmp_ne_u32_e32 vcc, 0, v2
	s_cbranch_vccnz .LBB0_567
	s_add_u32 s8, s64, 0x1b00200
	s_addc_u32 s9, s65, 0
	s_add_u32 s10, s64, 0x1b00400
	s_addc_u32 s11, s65, 0
	s_add_u32 s12, s64, 0x1b00500
	s_addc_u32 s13, s65, 0
	s_add_u32 s14, s64, 0x1b00600
	s_addc_u32 s15, s65, 0
	s_add_u32 s16, s64, 0x1b00700
	s_addc_u32 s17, s65, 0
	s_add_u32 s18, s64, 0x1b00800
	s_addc_u32 s19, s65, 0
	s_add_u32 s20, s64, 0x1b00900
	s_addc_u32 s21, s65, 0
	s_add_u32 s22, s64, 0x1b00a00
	s_addc_u32 s23, s65, 0
	s_add_u32 s24, s64, 0x1b00b00
	s_addc_u32 s25, s65, 0
	s_add_u32 s26, s64, 0x1b00c00
	s_addc_u32 s27, s65, 0
	s_add_u32 s28, s64, 0x1b00d00
	s_addc_u32 s29, s65, 0
	s_add_u32 s30, s64, 0x1b00e00
	s_addc_u32 s31, s65, 0
	s_add_u32 s34, s64, 0x1b00f00
	s_addc_u32 s35, s65, 0
	s_add_u32 s36, s64, 0x1b01000
	s_addc_u32 s37, s65, 0
	s_add_u32 s38, s64, 0x1b01100
	s_addc_u32 s39, s65, 0
	s_add_u32 s40, s64, 0x1b01200
	s_addc_u32 s41, s65, 0
	s_mul_i32 s0, s67, s77
	s_add_u32 s42, s64, 0x1b01300
	s_mul_i32 s0, s0, s66
	s_addc_u32 s43, s65, 0
	s_mov_b32 s1, 1
	v_mov_b32_e32 v16, 0
	s_branch .LBB0_555
